# prep U-row loop double-buffered (next row loads issued before current row stores, scalar address calc)
# baseline (speedup 1.0000x reference)
.LBB0_7:
	v_lshl_add_u32 v136, s57, 3, v6
	s_mov_b32 s2, 0x8900
	v_cmp_gt_i32_e32 vcc, s2, v136
	v_lshlrev_b32_e32 v140, 4, v138
	v_mbcnt_lo_u32_b32 v129, -1, 0
	s_and_saveexec_b64 s[6:7], vcc
	s_cbranch_execz .LBB0_22
	v_or_b32_e32 v16, 0x100, v138
	v_mov_b32_e32 v3, 0
	v_or_b32_e32 v18, 0x140, v138
	v_lshlrev_b32_e32 v2, 4, v16
	v_or_b32_e32 v20, 0x180, v138
	v_lshl_add_u64 v[6:7], s[48:49], 0, v[2:3]
	v_lshlrev_b32_e32 v2, 4, v18
	v_or_b32_e32 v22, 0x1c0, v138
	v_lshl_add_u64 v[8:9], s[48:49], 0, v[2:3]
	v_lshlrev_b32_e32 v2, 4, v20
	v_mbcnt_hi_u32_b32 v35, -1, v129
	v_mov_b32_e32 v141, v3
	v_lshl_add_u64 v[10:11], s[48:49], 0, v[2:3]
	v_lshlrev_b32_e32 v2, 4, v22
	v_and_b32_e32 v17, 64, v35
	s_lshl_b32 s2, s3, 3
	v_lshl_add_u64 v[4:5], s[48:49], 0, v[140:141]
	v_lshl_add_u64 v[12:13], s[48:49], 0, v[2:3]
	s_mov_b64 s[8:9], 0
	s_movk_i32 s18, 0x1080
	v_mov_b64_e32 v[14:15], s[70:71]
	s_mov_b32 s19, 0x8820
	s_mov_b32 s20, 0x801f
	s_mov_b32 s21, 0x7fe007ff
	s_movk_i32 s22, 0xbff0
	v_lshlrev_b32_e32 v16, 4, v16
	v_lshlrev_b32_e32 v18, 4, v18
	v_lshlrev_b32_e32 v20, 4, v20
	v_lshlrev_b32_e32 v22, 4, v22
	s_mov_b32 s10, 0
	v_mov_b32_e32 v34, 0x358637bd
	s_mov_b32 s23, 0x800000
	s_mov_b32 s24, 0x88ff
	v_lshlrev_b32_e32 v2, 4, v138
	v_xor_b32_e32 v36, 16, v35
	v_add_u32_e32 v37, 64, v17
	v_xor_b32_e32 v38, 32, v35
	v_lshlrev_b32_e32 v24, 3, v138
	v_mov_b32_e32 v39, v136
	global_load_dwordx4 v[182:185], v[4:5], off
	global_load_dwordx4 v[186:189], v[4:5], off offset:1024
	global_load_dwordx4 v[190:193], v[4:5], off offset:2048
	global_load_dwordx4 v[194:197], v[4:5], off offset:3072
	global_load_dwordx4 v[198:201], v[6:7], off
	global_load_dwordx4 v[202:205], v[8:9], off
	global_load_dwordx4 v[206:209], v[10:11], off
	global_load_dwordx4 v[210:213], v[12:13], off
	v_readfirstlane_b32 s26, v39
	s_cmp_lt_i32 s26, 0x8820
	s_cbranch_scc0 .Lpdb0_skip
	s_cmp_lt_i32 s26, 0x8020
	s_cbranch_scc0 .Lpdb0_sample
	s_cmp_ge_i32 s26, 0x4010
	s_cselect_b32 s27, 0x4010, 0
	s_cselect_b32 s28, 0x4000, 0
	s_sub_i32 s27, s26, s27
	s_cmp_lt_i32 s27, 16
	s_cbranch_scc0 .Lpdb0_prompt
	s_lshl_b32 s27, s27, 13
	s_add_u32 s34, s46, s27
	s_addc_u32 s35, s47, 0
	s_branch .Lpdb0_go
.Lpdb0_prompt:
	s_add_i32 s27, s27, s28
	s_sub_i32 s27, s27, 16
	s_lshl_b32 s27, s27, 13
	s_add_u32 s34, s36, s27
	s_addc_u32 s35, s37, 0
	s_branch .Lpdb0_go
.Lpdb0_sample:
	s_sub_i32 s27, s26, 0x8020
	s_lshl_b32 s27, s27, 13
	s_add_u32 s34, s38, s27
	s_addc_u32 s35, s39, 0
.Lpdb0_go:
	s_add_u32 s32, s34, 0x1000
	s_addc_u32 s33, s35, 0
	global_load_dwordx4 v[214:217], v2, s[34:35]
	global_load_dwordx4 v[218:221], v2, s[34:35] offset:1024
	global_load_dwordx4 v[222:225], v2, s[34:35] offset:2048
	global_load_dwordx4 v[226:229], v2, s[34:35] offset:3072
	global_load_dwordx4 v[230:233], v2, s[32:33]
	global_load_dwordx4 v[234:237], v2, s[32:33] offset:1024
	global_load_dwordx4 v[238:241], v2, s[32:33] offset:2048
	global_load_dwordx4 v[242:245], v2, s[32:33] offset:3072
.Lpdb0_skip:
	s_waitcnt vmcnt(0)
	s_branch .LBB0_10

.LBB0_19:
	s_or_b64 exec, exec, s[14:15]
	s_waitcnt vmcnt(8)
	v_mov_b64_e32 v[28:29], v[214:215]
	v_mov_b64_e32 v[30:31], v[216:217]
	v_mov_b64_e32 v[40:41], v[218:219]
	v_mov_b64_e32 v[42:43], v[220:221]
	v_mov_b64_e32 v[44:45], v[222:223]
	v_mov_b64_e32 v[46:47], v[224:225]
	v_mov_b64_e32 v[48:49], v[226:227]
	v_mov_b64_e32 v[50:51], v[228:229]
	v_mov_b64_e32 v[52:53], v[230:231]
	v_mov_b64_e32 v[54:55], v[232:233]
	v_mov_b64_e32 v[56:57], v[234:235]
	v_mov_b64_e32 v[58:59], v[236:237]
	v_mov_b64_e32 v[60:61], v[238:239]
	v_mov_b64_e32 v[62:63], v[240:241]
	v_mov_b64_e32 v[64:65], v[242:243]
	v_mov_b64_e32 v[66:67], v[244:245]
	v_cmp_lt_i32_e32 vcc, v36, v37
	v_pk_mul_f32 v[72:73], v[28:29], v[28:29]
	v_pk_mul_f32 v[76:77], v[40:41], v[40:41]
	v_pk_mul_f32 v[32:33], v[30:31], v[30:31]
	v_pk_mul_f32 v[74:75], v[42:43], v[42:43]
	v_pk_mul_f32 v[80:81], v[44:45], v[44:45]
	v_add_f32_e32 v19, v76, v77
	v_add_f32_e32 v21, v72, v73
	v_pk_mul_f32 v[78:79], v[46:47], v[46:47]
	v_pk_mul_f32 v[84:85], v[48:49], v[48:49]
	v_mov_b32_e32 v92, v53
	v_mov_b32_e32 v93, v57
	v_add_f32_e32 v23, v80, v81
	v_add_f32_e32 v19, v19, v74
	v_add_f32_e32 v21, v21, v32
	v_pk_mul_f32 v[82:83], v[50:51], v[50:51]
	v_mov_b32_e32 v90, v52
	v_mov_b32_e32 v91, v56
	v_pk_mul_f32 v[92:93], v[92:93], v[92:93]
	v_add_f32_e32 v25, v84, v85
	v_add_f32_e32 v23, v23, v78
	v_add_f32_e32 v19, v19, v75
	v_add_f32_e32 v21, v21, v33
	v_mov_b32_e32 v86, v54
	v_mov_b32_e32 v87, v58
	v_mov_b32_e32 v100, v61
	v_mov_b32_e32 v101, v65
	v_pk_fma_f32 v[72:73], v[90:91], v[90:91], v[92:93]
	v_add_f32_e32 v25, v25, v82
	v_add_f32_e32 v23, v23, v79
	v_add_f32_e32 v19, v21, v19
	v_mov_b32_e32 v88, v55
	v_mov_b32_e32 v89, v59
	v_mov_b32_e32 v98, v60
	v_mov_b32_e32 v99, v64
	v_pk_mul_f32 v[100:101], v[100:101], v[100:101]
	v_pk_fma_f32 v[72:73], v[86:87], v[86:87], v[72:73]
	v_add_f32_e32 v25, v25, v83
	v_add_f32_e32 v19, v19, v23
	v_mov_b32_e32 v94, v62
	v_mov_b32_e32 v95, v66
	v_pk_fma_f32 v[76:77], v[98:99], v[98:99], v[100:101]
	v_pk_fma_f32 v[32:33], v[88:89], v[88:89], v[72:73]
	v_add_f32_e32 v19, v19, v25
	v_mov_b32_e32 v96, v63
	v_mov_b32_e32 v97, v67
	v_pk_fma_f32 v[76:77], v[94:95], v[94:95], v[76:77]
	v_add_f32_e32 v19, v19, v32
	v_pk_fma_f32 v[72:73], v[96:97], v[96:97], v[76:77]
	v_add_f32_e32 v19, v19, v33
	v_add_f32_e32 v19, v19, v72
	v_add_f32_e32 v19, v19, v73
	v_cndmask_b32_e32 v17, v35, v36, vcc
	v_lshlrev_b32_e32 v17, 2, v17
	v_add_f32_dpp v19, v19, v19 quad_perm:[1,0,3,2] row_mask:0xf bank_mask:0xf bound_ctrl:1
	v_cmp_lt_i32_e32 vcc, v38, v37
	v_mov_b32_e32 v25, v3
	v_add_f32_dpp v19, v19, v19 quad_perm:[2,3,0,1] row_mask:0xf bank_mask:0xf bound_ctrl:1
	v_cndmask_b32_e32 v21, v35, v38, vcc
	v_lshlrev_b32_e32 v21, 2, v21
	v_add_f32_dpp v19, v19, v19 row_half_mirror row_mask:0xf bank_mask:0xf bound_ctrl:1
	v_lshl_add_u64 v[32:33], v[26:27], 0, v[24:25]
	s_nop 0
	v_add_f32_dpp v19, v19, v19 row_mirror row_mask:0xf bank_mask:0xf bound_ctrl:1
	ds_bpermute_b32 v17, v17, v19
	s_waitcnt lgkmcnt(0)
	v_add_f32_e32 v17, v19, v17
	ds_bpermute_b32 v19, v21, v17
	s_waitcnt lgkmcnt(0)
	v_add_f32_e32 v17, v17, v19
	v_fmamk_f32 v17, v17, 0x3a000000, v34
	v_mul_f32_e32 v19, 0x4b800000, v17
	v_cmp_gt_f32_e32 vcc, s23, v17
	s_nop 1
	v_cndmask_b32_e32 v17, v17, v19, vcc
	v_rsq_f32_e32 v17, v17
	s_nop 0
	v_mul_f32_e32 v19, 0x45800000, v17
	v_cndmask_b32_e32 v72, v17, v19, vcc
	v_pk_mul_f32 v[26:27], v[28:29], v[72:73] op_sel_hi:[1,0]
	v_pk_mul_f32 v[28:29], v[30:31], v[72:73] op_sel_hi:[1,0]
	v_pk_mul_f32 v[26:27], v[182:183], v[26:27]
	v_pk_mul_f32 v[28:29], v[184:185], v[28:29]
	v_cvt_pk_bf16_f32 v26, v26, v27
	v_cvt_pk_bf16_f32 v27, v28, v29
	v_readfirstlane_b32 s26, v39
	s_add_i32 s26, s26, s2
	s_cmp_lt_i32 s26, 0x8820
	s_cbranch_scc0 .Lpdb1_skip
	s_cmp_lt_i32 s26, 0x8020
	s_cbranch_scc0 .Lpdb1_sample
	s_cmp_ge_i32 s26, 0x4010
	s_cselect_b32 s27, 0x4010, 0
	s_cselect_b32 s28, 0x4000, 0
	s_sub_i32 s27, s26, s27
	s_cmp_lt_i32 s27, 16
	s_cbranch_scc0 .Lpdb1_prompt
	s_lshl_b32 s27, s27, 13
	s_add_u32 s34, s46, s27
	s_addc_u32 s35, s47, 0
	s_branch .Lpdb1_go

.Lpdb1_skip:
	global_store_dwordx2 v[32:33], v[26:27], off
	v_pk_mul_f32 v[30:31], v[40:41], v[72:73] op_sel_hi:[1,0]
	v_pk_mul_f32 v[40:41], v[42:43], v[72:73] op_sel_hi:[1,0]
	v_pk_mul_f32 v[26:27], v[186:187], v[30:31]
	v_pk_mul_f32 v[28:29], v[188:189], v[40:41]
	v_cvt_pk_bf16_f32 v26, v26, v27
	v_cvt_pk_bf16_f32 v27, v28, v29
	global_store_dwordx2 v[32:33], v[26:27], off offset:512
	v_pk_mul_f32 v[30:31], v[44:45], v[72:73] op_sel_hi:[1,0]
	v_pk_mul_f32 v[40:41], v[46:47], v[72:73] op_sel_hi:[1,0]
	v_pk_mul_f32 v[26:27], v[30:31], v[190:191]
	v_pk_mul_f32 v[28:29], v[40:41], v[192:193]
	v_cvt_pk_bf16_f32 v26, v26, v27
	v_cvt_pk_bf16_f32 v27, v28, v29
	global_store_dwordx2 v[32:33], v[26:27], off offset:1024
	v_pk_mul_f32 v[30:31], v[48:49], v[72:73] op_sel_hi:[1,0]
	v_pk_mul_f32 v[40:41], v[50:51], v[72:73] op_sel_hi:[1,0]
	v_pk_mul_f32 v[26:27], v[30:31], v[194:195]
	v_pk_mul_f32 v[28:29], v[40:41], v[196:197]
	v_cvt_pk_bf16_f32 v26, v26, v27
	v_cvt_pk_bf16_f32 v27, v28, v29
	global_store_dwordx2 v[32:33], v[26:27], off offset:1536
	v_pk_mul_f32 v[30:31], v[52:53], v[72:73] op_sel_hi:[1,0]
	v_pk_mul_f32 v[40:41], v[54:55], v[72:73] op_sel_hi:[1,0]
	v_pk_mul_f32 v[26:27], v[30:31], v[198:199]
	v_pk_mul_f32 v[28:29], v[40:41], v[200:201]
	v_cvt_pk_bf16_f32 v26, v26, v27
	v_cvt_pk_bf16_f32 v27, v28, v29
	global_store_dwordx2 v[32:33], v[26:27], off offset:2048
	v_pk_mul_f32 v[30:31], v[56:57], v[72:73] op_sel_hi:[1,0]
	v_pk_mul_f32 v[40:41], v[58:59], v[72:73] op_sel_hi:[1,0]
	v_pk_mul_f32 v[26:27], v[30:31], v[202:203]
	v_pk_mul_f32 v[28:29], v[40:41], v[204:205]
	v_cvt_pk_bf16_f32 v26, v26, v27
	v_cvt_pk_bf16_f32 v27, v28, v29
	global_store_dwordx2 v[32:33], v[26:27], off offset:2560
	v_pk_mul_f32 v[30:31], v[60:61], v[72:73] op_sel_hi:[1,0]
	v_pk_mul_f32 v[40:41], v[62:63], v[72:73] op_sel_hi:[1,0]
	v_pk_mul_f32 v[26:27], v[30:31], v[206:207]
	v_pk_mul_f32 v[28:29], v[40:41], v[208:209]
	v_cvt_pk_bf16_f32 v26, v26, v27
	v_cvt_pk_bf16_f32 v27, v28, v29
	global_store_dwordx2 v[32:33], v[26:27], off offset:3072
	v_pk_mul_f32 v[30:31], v[64:65], v[72:73] op_sel_hi:[1,0]
	v_pk_mul_f32 v[40:41], v[66:67], v[72:73] op_sel_hi:[1,0]
	v_pk_mul_f32 v[26:27], v[30:31], v[210:211]
	v_pk_mul_f32 v[28:29], v[40:41], v[212:213]
	v_cvt_pk_bf16_f32 v26, v26, v27
	v_cvt_pk_bf16_f32 v27, v28, v29
	global_store_dwordx2 v[32:33], v[26:27], off offset:3584
